# P5 and P6 K-loop heads pinned to the 64-byte-line offsets they had in the best version (24 and 8 bytes), on top of the P5 canonicalisation removal
# speedup vs baseline: 1.0041x; 1.0041x over previous
; template <class Epi, class Sched, bool ALIGN_EPI = false, bool SP2 = false>
; __device__ __forceinline__ void gemm_phase(PG8_LAS unsigned char* lds, const Gemm g, const Sched& S, const Epi& E) {
;     ...
;         const bool has_next = S.next(ui + 1, nxt);
;         const char* nA = has_next ? (const char*)g.A + (size_t)nxt.pm * tstep : cA; const char* nB = has_next ? (const char*)g.Bt + (size_t)nxt.pn * tstep : cB;
;         for (int t = 0; t < nt; t += 2) {
;             const bool last = (t == nt - 2);
;             const char* a1 = cA + (size_t)(t + 1) * kstep;
;             const char* a2 = last ? nA : cA + (size_t)(t + 2) * kstep; const char* b2 = last ? nB : cB + (size_t)(t + 2) * kstep;
;             const char* a3 = a2 + kstep; const char* b3 = b2 + kstep;
;     ...
; #pragma unroll
;         for (int a = 0; a < 2; ++a)
; #pragma unroll
;             for (int b = 0; b < 2; ++b)
; #pragma unroll
;                 for (int m = 0; m < 4; ++m)
; #pragma unroll
;                     for (int n = 0; n < 2; ++n) acc[a][b][m][n] = (f32x4){0.f, 0.f, 0.f, 0.f};
;         cur = nxt; cA = nA; cB = nB; ++ui;
.LBB0_626:
	s_ashr_i32 s41, s40, 31
	s_lshl_b64 s[42:43], s[40:41], 20
	s_add_u32 s42, s26, s42
	s_addc_u32 s43, s27, s43
	s_and_b64 s[44:45], s[0:1], exec
	s_cselect_b32 s41, s43, s47
	s_cselect_b32 s88, s42, s46
	s_ashr_i32 s31, s30, 31
	s_lshl_b64 s[44:45], s[30:31], 20
	s_add_u32 s44, s56, s44
	s_addc_u32 s45, s57, s45
	s_and_b64 s[52:53], s[0:1], exec
	s_cselect_b32 s90, s45, s51
	s_cselect_b32 s91, s44, s50
	s_lshl_b32 s89, s48, 8
	s_ashr_i32 s48, s49, 2
	s_lshl_b32 s31, s49, 8
	s_ashr_i32 s49, s48, 31
	s_add_i32 s92, s89, s67
	s_lshl_b64 s[52:53], s[48:49], 26
	s_add_u32 s52, s65, s52
	s_addc_u32 s53, s66, s53
	s_and_b32 s54, s31, 0x300
	v_or_b32_e32 v0, s54, v157
	v_lshlrev_b32_e32 v0, 1, v0
	v_mov_b32_e32 v2, v1
	v_mov_b32_e32 v3, v1
	v_lshl_add_u64 v[148:149], s[52:53], 0, v[0:1]
	s_add_u32 s93, s50, 0x100
	v_mov_b32_e32 v0, v1
	v_mov_b64_e32 v[6:7], v[2:3]
	v_mov_b64_e32 v[10:11], v[2:3]
	v_mov_b64_e32 v[22:23], v[2:3]
	v_mov_b64_e32 v[26:27], v[2:3]
	v_mov_b64_e32 v[38:39], v[2:3]
	v_mov_b64_e32 v[42:43], v[2:3]
	v_mov_b64_e32 v[54:55], v[2:3]
	v_mov_b64_e32 v[58:59], v[2:3]
	v_mov_b64_e32 v[14:15], v[2:3]
	v_mov_b64_e32 v[18:19], v[2:3]
	v_mov_b64_e32 v[30:31], v[2:3]
	v_mov_b64_e32 v[34:35], v[2:3]
	v_mov_b64_e32 v[46:47], v[2:3]
	v_mov_b64_e32 v[50:51], v[2:3]
	v_mov_b64_e32 v[62:63], v[2:3]
	v_mov_b64_e32 v[66:67], v[2:3]
	v_mov_b64_e32 v[70:71], v[2:3]
	v_mov_b64_e32 v[74:75], v[2:3]
	v_mov_b64_e32 v[86:87], v[2:3]
	v_mov_b64_e32 v[90:91], v[2:3]
	v_mov_b64_e32 v[102:103], v[2:3]
	v_mov_b64_e32 v[106:107], v[2:3]
	v_mov_b64_e32 v[118:119], v[2:3]
	v_mov_b64_e32 v[122:123], v[2:3]
	v_mov_b64_e32 v[78:79], v[2:3]
	v_mov_b64_e32 v[82:83], v[2:3]
	v_mov_b64_e32 v[94:95], v[2:3]
	v_mov_b64_e32 v[98:99], v[2:3]
	v_mov_b64_e32 v[110:111], v[2:3]
	v_mov_b64_e32 v[114:115], v[2:3]
	v_mov_b64_e32 v[126:127], v[2:3]
	v_mov_b64_e32 v[130:131], v[2:3]
	v_lshl_add_u64 v[150:151], s[46:47], 0, v[140:141]
	v_lshl_add_u64 v[152:153], s[46:47], 0, v[142:143]
	s_addc_u32 s94, s51, 0
	s_mov_b32 s95, -2
	s_mov_b64 s[50:51], 0
	v_mov_b64_e32 v[4:5], v[0:1]
	v_mov_b64_e32 v[8:9], v[0:1]
	v_mov_b64_e32 v[20:21], v[0:1]
	v_mov_b64_e32 v[24:25], v[0:1]
	v_mov_b64_e32 v[36:37], v[0:1]
	v_mov_b64_e32 v[40:41], v[0:1]
	v_mov_b64_e32 v[52:53], v[0:1]
	v_mov_b64_e32 v[56:57], v[0:1]
	v_mov_b64_e32 v[12:13], v[0:1]
	v_mov_b64_e32 v[16:17], v[0:1]
	v_mov_b64_e32 v[28:29], v[0:1]
	v_mov_b64_e32 v[32:33], v[0:1]
	v_mov_b64_e32 v[44:45], v[0:1]
	v_mov_b64_e32 v[48:49], v[0:1]
	v_mov_b64_e32 v[60:61], v[0:1]
	v_mov_b64_e32 v[64:65], v[0:1]
	v_mov_b64_e32 v[68:69], v[0:1]
	v_mov_b64_e32 v[72:73], v[0:1]
	v_mov_b64_e32 v[84:85], v[0:1]
	v_mov_b64_e32 v[88:89], v[0:1]
	v_mov_b64_e32 v[100:101], v[0:1]
	v_mov_b64_e32 v[104:105], v[0:1]
	v_mov_b64_e32 v[116:117], v[0:1]
	v_mov_b64_e32 v[120:121], v[0:1]
	v_mov_b64_e32 v[76:77], v[0:1]
	v_mov_b64_e32 v[80:81], v[0:1]
	v_mov_b64_e32 v[92:93], v[0:1]
	v_mov_b64_e32 v[96:97], v[0:1]
	v_mov_b64_e32 v[108:109], v[0:1]
	v_mov_b64_e32 v[112:113], v[0:1]
	v_mov_b64_e32 v[124:125], v[0:1]
	v_mov_b64_e32 v[128:129], v[0:1]
	s_branch .LBB0_628
	.p2align	6
	s_nop 0
	s_nop 0
	s_nop 0
	s_nop 0
	s_nop 0
	s_nop 0

; template <class Epi, class Sched, bool ALIGN_EPI = false, bool SP2 = false>
; __device__ __forceinline__ void gemm_phase(PG8_LAS unsigned char* lds, const Gemm g, const Sched& S, const Epi& E) {
;     ...
; #pragma unroll
;         for (int a = 0; a < 2; ++a)
; #pragma unroll
;             for (int b = 0; b < 2; ++b)
; #pragma unroll
;                 for (int m = 0; m < 4; ++m)
; #pragma unroll
;                     for (int n = 0; n < 2; ++n) acc[a][b][m][n] = (f32x4){0.f, 0.f, 0.f, 0.f};
;         cur = nxt; cA = nA; cB = nB; ++ui;
.LBB0_663:
	s_ashr_i32 s21, s20, 31
	s_lshl_b64 s[22:23], s[20:21], 20
	s_add_u32 s22, s38, s22
	s_addc_u32 s23, s39, s23
	s_and_b64 s[24:25], s[4:5], exec
	s_cselect_b32 s21, s23, s43
	s_cselect_b32 s31, s22, s42
	s_ashr_i32 s19, s18, 31
	s_lshl_b64 s[24:25], s[18:19], 20
	s_add_u32 s24, s3, s24
	s_addc_u32 s25, s48, s25
	s_and_b64 s[46:47], s[4:5], exec
	s_cselect_b32 s19, s25, s45
	s_cselect_b32 s60, s24, s44
	s_add_u32 s42, s42, 0x80080
	s_addc_u32 s43, s43, 0
	s_add_u32 s61, s44, 0x100
	v_mov_b32_e32 v0, 0
	s_addc_u32 s62, s45, 0
	s_mov_b32 s63, -2
	s_waitcnt lgkmcnt(0)
	v_mov_b32_e32 v1, v0
	v_mov_b32_e32 v2, v0
	v_mov_b32_e32 v3, v0
	v_mov_b32_e32 v4, v0
	v_mov_b32_e32 v5, v0
	v_mov_b32_e32 v6, v0
	v_mov_b32_e32 v7, v0
	v_mov_b32_e32 v16, v0
	v_mov_b32_e32 v17, v0
	v_mov_b32_e32 v18, v0
	v_mov_b32_e32 v19, v0
	v_mov_b32_e32 v20, v0
	v_mov_b32_e32 v21, v0
	v_mov_b32_e32 v22, v0
	v_mov_b32_e32 v23, v0
	v_mov_b32_e32 v32, v0
	v_mov_b32_e32 v33, v0
	v_mov_b32_e32 v34, v0
	v_mov_b32_e32 v35, v0
	v_mov_b32_e32 v36, v0
	v_mov_b32_e32 v37, v0
	v_mov_b32_e32 v38, v0
	v_mov_b32_e32 v39, v0
	v_mov_b32_e32 v48, v0
	v_mov_b32_e32 v49, v0
	v_mov_b32_e32 v50, v0
	v_mov_b32_e32 v51, v0
	v_mov_b32_e32 v52, v0
	v_mov_b32_e32 v53, v0
	v_mov_b32_e32 v54, v0
	v_mov_b32_e32 v55, v0
	v_mov_b32_e32 v8, v0
	v_mov_b32_e32 v9, v0
	v_mov_b32_e32 v10, v0
	v_mov_b32_e32 v11, v0
	v_mov_b32_e32 v12, v0
	v_mov_b32_e32 v13, v0
	v_mov_b32_e32 v14, v0
	v_mov_b32_e32 v15, v0
	v_mov_b32_e32 v24, v0
	v_mov_b32_e32 v25, v0
	v_mov_b32_e32 v26, v0
	v_mov_b32_e32 v27, v0
	v_mov_b32_e32 v28, v0
	v_mov_b32_e32 v29, v0
	v_mov_b32_e32 v30, v0
	v_mov_b32_e32 v31, v0
	v_mov_b32_e32 v40, v0
	v_mov_b32_e32 v41, v0
	v_mov_b32_e32 v42, v0
	v_mov_b32_e32 v43, v0
	v_mov_b32_e32 v44, v0
	v_mov_b32_e32 v45, v0
	v_mov_b32_e32 v46, v0
	v_mov_b32_e32 v47, v0
	v_mov_b32_e32 v56, v0
	v_mov_b32_e32 v57, v0
	v_mov_b32_e32 v58, v0
	v_mov_b32_e32 v59, v0
	v_mov_b32_e32 v60, v0
	v_mov_b32_e32 v61, v0
	v_mov_b32_e32 v62, v0
	v_mov_b32_e32 v63, v0
	v_mov_b32_e32 v64, v0
	v_mov_b32_e32 v65, v0
	v_mov_b32_e32 v66, v0
	v_mov_b32_e32 v67, v0
	v_mov_b32_e32 v68, v0
	v_mov_b32_e32 v69, v0
	v_mov_b32_e32 v70, v0
	v_mov_b32_e32 v71, v0
	v_mov_b32_e32 v80, v0
	v_mov_b32_e32 v81, v0
	v_mov_b32_e32 v82, v0
	v_mov_b32_e32 v83, v0
	v_mov_b32_e32 v84, v0
	v_mov_b32_e32 v85, v0
	v_mov_b32_e32 v86, v0
	v_mov_b32_e32 v87, v0
	v_mov_b32_e32 v96, v0
	v_mov_b32_e32 v97, v0
	v_mov_b32_e32 v98, v0
	v_mov_b32_e32 v99, v0
	v_mov_b32_e32 v100, v0
	v_mov_b32_e32 v101, v0
	v_mov_b32_e32 v102, v0
	v_mov_b32_e32 v103, v0
	v_mov_b32_e32 v112, v0
	v_mov_b32_e32 v113, v0
	v_mov_b32_e32 v114, v0
	v_mov_b32_e32 v115, v0
	v_mov_b32_e32 v116, v0
	v_mov_b32_e32 v117, v0
	v_mov_b32_e32 v118, v0
	v_mov_b32_e32 v119, v0
	v_mov_b32_e32 v72, v0
	v_mov_b32_e32 v73, v0
	v_mov_b32_e32 v74, v0
	v_mov_b32_e32 v75, v0
	v_mov_b32_e32 v76, v0
	v_mov_b32_e32 v77, v0
	v_mov_b32_e32 v78, v0
	v_mov_b32_e32 v79, v0
	v_mov_b32_e32 v88, v0
	v_mov_b32_e32 v89, v0
	v_mov_b32_e32 v90, v0
	v_mov_b32_e32 v91, v0
	v_mov_b32_e32 v92, v0
	v_mov_b32_e32 v93, v0
	v_mov_b32_e32 v94, v0
	v_mov_b32_e32 v95, v0
	v_mov_b32_e32 v104, v0
	v_mov_b32_e32 v105, v0
	v_mov_b32_e32 v106, v0
	v_mov_b32_e32 v107, v0
	v_mov_b32_e32 v108, v0
	v_mov_b32_e32 v109, v0
	v_mov_b32_e32 v110, v0
	v_mov_b32_e32 v111, v0
	v_mov_b32_e32 v120, v0
	v_mov_b32_e32 v121, v0
	v_mov_b32_e32 v122, v0
	v_mov_b32_e32 v123, v0
	v_mov_b32_e32 v124, v0
	v_mov_b32_e32 v125, v0
	v_mov_b32_e32 v126, v0
	v_mov_b32_e32 v127, v0
	.p2align	6
	s_nop 0
	s_nop 0
